# ssd_scan: wave-0 cumulative sum via DPP row scan instead of 6 ds_bpermute round trips (f32, different summation order) + posbias load batching + attn_sw edits
# baseline (speedup 1.0000x reference)
; #define LAS __attribute__((address_space(3)))
; __device__ __forceinline__ unsigned pk2(float lo, float hi) { return f2bf(lo) | (f2bf(hi) << 16); }
; #define SSD_CS(buf_) do { if (w == 0) { float a = rdt * Ah; \
;             _Pragma("unroll") for (int o = 1; o < 64; o <<= 1) { const float v = __shfl_up(a, o); if (lane >= o) a += v; } \
;             ((LAS float*)(L + SS_CS))[(buf_) * 64 + lane] = a; ((LAS float*)(L + SS_DTS))[(buf_) * 64 + lane] = rdt; } } while (0)
; #define SSD_LDT(t0_) do { if (w == 0) rdt = DT[((size_t)b * SEQ + (t0_) + lane) * 64 + h]; } while (0)
; __device__ __forceinline__ void ssd_scan_mfma(const Ctx& c, bf16* X2, const float* DT, const float* a_log, const float* dskip, bool do_store) {
;     ...
;             __syncthreads();
; #pragma unroll
;             for (int e = 0; e < 2; ++e) { const int cc = tid + 512 * e;
;                 *(LAS v4u*)(L + SS_B + (cc >> 4) * 272 + (cc & 15) * 16) = rB[e]; *(LAS v4u*)(L + SS_C + (cc >> 4) * 272 + (cc & 15) * 16) = rC[e]; }
;             *(LAS v4u*)(L + SS_XR + (tid >> 3) * 144 + (tid & 7) * 16) = rXR;
;             { const int sr = tid >> 3, p8 = tid & 7; const float fd = DTS[sr], fw = fd * __expf(CS[63] - CS[sr]);
;               float xv[8];
; #pragma unroll
;               for (int j = 0; j < 4; ++j) { xv[2 * j] = bflo(rXR[j]); xv[2 * j + 1] = bfhi(rXR[j]); }
;               v4u o1, o2; o1.x = pk2(xv[0] * fd, xv[1] * fd); o1.y = pk2(xv[2] * fd, xv[3] * fd); o1.z = pk2(xv[4] * fd, xv[5] * fd); o1.w = pk2(xv[6] * fd, xv[7] * fd);
;               o2.x = pk2(xv[0] * fw, xv[1] * fw); o2.y = pk2(xv[2] * fw, xv[3] * fw); o2.z = pk2(xv[4] * fw, xv[5] * fw); o2.w = pk2(xv[6] * fw, xv[7] * fw);
;               *(LAS v4u*)(L + SS_XD + sr * 144 + p8 * 16) = o1; *(LAS v4u*)(L + SS_XW + sr * 144 + p8 * 16) = o2; }
;             if (ch + 1 < SEQ / 64) { SSD_LOAD(t0 + 64); SSD_CS(cb ^ 1); if (ch + 2 < SEQ / 64) SSD_LDT(t0 + 128); }
.LBB0_469:
	s_and_b32 s96, s63, 1
	s_lshl_b32 s52, s96, 8
	s_add_i32 s65, s52, 0
	s_add_i32 s65, s65, 0x17c00
	s_waitcnt lgkmcnt(0)
	s_barrier
	s_waitcnt vmcnt(4)
	ds_write_b128 v130, v[30:33]
	s_waitcnt vmcnt(3)
	ds_write_b128 v130, v[26:29] offset:17408
	s_waitcnt vmcnt(2)
	ds_write_b128 v131, v[38:41]
	s_waitcnt vmcnt(1)
	ds_write_b128 v131, v[34:37] offset:17408
	s_waitcnt vmcnt(0)
	ds_write_b128 v132, v[22:25] offset:34816
	v_add_u32_e32 v26, s52, v112
	v_mov_b32_e32 v27, s65
	v_lshl_add_u32 v28, v108, 2, s65
	ds_read_b32 v26, v26
	ds_read_b32 v27, v27 offset:252
	ds_read_b32 v28, v28
	v_lshlrev_b32_e32 v31, 16, v23
	v_lshlrev_b32_e32 v30, 16, v22
	v_and_b32_e32 v23, 0xffff0000, v23
	v_and_b32_e32 v22, 0xffff0000, v22
	s_waitcnt lgkmcnt(0)
	v_sub_f32_e32 v27, v27, v28
	v_mul_f32_e32 v27, 0x3fb8aa3b, v27
	v_exp_f32_e32 v27, v27
	v_and_b32_e32 v41, 0xffff0000, v25
	v_and_b32_e32 v40, 0xffff0000, v24
	v_lshlrev_b32_e32 v39, 16, v25
	v_mul_f32_e32 v28, v26, v27
	v_pk_mul_f32 v[34:35], v[26:27], v[22:23] op_sel_hi:[0,1]
	v_lshlrev_b32_e32 v38, 16, v24
	v_pk_mul_f32 v[24:25], v[26:27], v[40:41] op_sel_hi:[0,1]
	v_pk_mul_f32 v[32:33], v[26:27], v[30:31] op_sel_hi:[0,1]
	v_pk_mul_f32 v[30:31], v[28:29], v[30:31] op_sel_hi:[0,1]
	v_pk_mul_f32 v[36:37], v[28:29], v[22:23] op_sel_hi:[0,1]
	v_pk_mul_f32 v[22:23], v[26:27], v[38:39] op_sel_hi:[0,1]
	v_bfe_u32 v26, v25, 16, 1
	v_bfe_u32 v27, v24, 16, 1
	v_bfe_u32 v29, v35, 16, 1
	v_bfe_u32 v42, v34, 16, 1
	v_add3_u32 v34, v34, v42, s88
	v_add3_u32 v29, v35, v29, s88
	v_add3_u32 v24, v24, v27, s88
	v_add3_u32 v25, v25, v26, s88
	v_bfe_u32 v26, v32, 16, 1
	v_bfe_u32 v27, v33, 16, 1
	v_bfe_u32 v35, v22, 16, 1
	v_bfe_u32 v42, v23, 16, 1
	v_add3_u32 v23, v23, v42, s88
	v_add3_u32 v22, v22, v35, s88
	v_add3_u32 v27, v33, v27, s88
	v_add3_u32 v26, v32, v26, s88
	v_lshrrev_b32_e32 v26, 16, v26
	v_lshrrev_b32_e32 v27, 16, v27
	v_lshrrev_b32_e32 v22, 16, v22
	v_lshrrev_b32_e32 v23, 16, v23
	v_and_or_b32 v25, v25, s87, v23
	v_and_or_b32 v24, v24, s87, v22
	v_and_or_b32 v23, v29, s87, v27
	v_and_or_b32 v22, v34, s87, v26
	v_pk_mul_f32 v[26:27], v[28:29], v[38:39] op_sel_hi:[0,1]
	v_pk_mul_f32 v[28:29], v[28:29], v[40:41] op_sel_hi:[0,1]
	s_load_dwordx2 s[4:5], s[68:69], 0x120
	v_bfe_u32 v32, v29, 16, 1
	v_bfe_u32 v33, v28, 16, 1
	v_bfe_u32 v34, v37, 16, 1
	v_bfe_u32 v35, v36, 16, 1
	v_add3_u32 v35, v36, v35, s88
	v_add3_u32 v34, v37, v34, s88
	v_add3_u32 v28, v28, v33, s88
	v_add3_u32 v29, v29, v32, s88
	v_bfe_u32 v32, v30, 16, 1
	v_bfe_u32 v33, v31, 16, 1
	v_bfe_u32 v36, v26, 16, 1
	v_bfe_u32 v37, v27, 16, 1
	v_add3_u32 v27, v27, v37, s88
	v_add3_u32 v26, v26, v36, s88
	v_add3_u32 v31, v31, v33, s88
	v_add3_u32 v30, v30, v32, s88
	v_lshrrev_b32_e32 v30, 16, v30
	v_lshrrev_b32_e32 v31, 16, v31
	v_lshrrev_b32_e32 v26, 16, v26
	v_lshrrev_b32_e32 v27, 16, v27
	v_and_or_b32 v29, v29, s87, v27
	v_and_or_b32 v28, v28, s87, v26
	v_and_or_b32 v27, v34, s87, v31
	v_and_or_b32 v26, v35, s87, v30
	ds_write_b128 v132, v[22:25] offset:44032
	ds_write_b128 v132, v[26:29] offset:53248
	s_waitcnt lgkmcnt(0)
	v_lshl_add_u64 v[22:23], s[4:5], 0, v[102:103]
	s_mov_b32 s52, 0x234c2000
	v_add_co_u32_e32 v22, vcc, s52, v22
	s_xor_b32 s76, s96, 1
	s_nop 0
	v_addc_co_u32_e32 v23, vcc, 0, v23, vcc
	global_load_dwordx4 v[30:33], v[22:23], off
	global_load_dwordx4 v[26:29], v[22:23], off offset:2048
	v_lshl_add_u64 v[22:23], s[4:5], 0, v[104:105]
	v_add_co_u32_e32 v22, vcc, 0x234c2000, v22
	s_mov_b64 s[6:7], s[68:69]
	s_nop 0
	v_addc_co_u32_e32 v23, vcc, 0, v23, vcc
	global_load_dwordx4 v[38:41], v[22:23], off
	global_load_dwordx4 v[34:37], v[22:23], off offset:2048
	v_lshl_add_u64 v[22:23], s[4:5], 0, v[100:101]
	global_load_dwordx4 v[22:25], v[22:23], off
	s_and_b64 vcc, exec, s[50:51]
	s_cbranch_vccnz .LBB0_471
	v_mul_f32_e64 v42, v93, -v138
	s_nop 1
	v_add_f32_dpp v42, v42, v42 row_shr:1 row_mask:0xf bank_mask:0xf
	s_nop 1
	v_add_f32_dpp v42, v42, v42 row_shr:2 row_mask:0xf bank_mask:0xf
	s_nop 1
	v_add_f32_dpp v42, v42, v42 row_shr:4 row_mask:0xf bank_mask:0xf
	s_nop 1
	v_add_f32_dpp v42, v42, v42 row_shr:8 row_mask:0xf bank_mask:0xf
	s_nop 1
	v_add_f32_dpp v42, v42, v42 row_bcast:15 row_mask:0xa bank_mask:0xf
	s_nop 1
	v_add_f32_dpp v42, v42, v42 row_bcast:31 row_mask:0xc bank_mask:0xf
	s_nop 1
	v_lshl_or_b32 v43, s76, 8, v109
	v_add_u32_e32 v43, 0, v43
	v_add_u32_e32 v44, 0x17c00, v43
	ds_write_b32 v44, v42
	v_add_u32_e32 v42, 0x17e00, v43
	ds_write_b32 v42, v93
